# finish phase: 4-row items (9 per workgroup, evenly dealt), ring of four load buffers, DPP per-head reduction
# speedup vs baseline: 1.0044x; 1.0044x over previous
; DI void unpack8(u32x4 v, float* o) { o[0] = lo16(v.x); o[1] = hi16(v.x); o[2] = lo16(v.y); o[3] = hi16(v.y); o[4] = lo16(v.z); o[5] = hi16(v.z); o[6] = lo16(v.w); o[7] = hi16(v.w); }
; DI int otid() { int t = threadIdx.x; asm volatile("" : "+v"(t)); return t; }
; #define ITEM_BEGIN { size_t z_ = 0; asm volatile("" : "+s"(z_)); q.ws = p.ws + z_; sm = smem + osgpr(0); }
; #define PHASE_BEGIN P q = p; { size_t z_ = 0; asm volatile("" : "+s"(z_)); q.ws = p.ws + z_; } unsigned char* sm = smem + osgpr(0); const int b1 = osgpr(bid); (void)sm; (void)b1;
; DI void finish_item(const P& p, int l, int r16) {
;     ...
;     const int tid = otid(); const int row0 = r16 * 16 + (tid >> 7) * 4, u = tid & 127, mx = u >> 6, hh = (u >> 4) & 3, sub = u & 15;
;     const int chn = 128 * hh + 8 * sub;
;     u32x4 ra[4], rb[4], rg[4];
; #pragma unroll
;     for (int k = 0; k < 4; ++k) {
;         ra[k] = __builtin_nontemporal_load((const u32x4*)(O + ((size_t)(mx * 2 + 0) * NROW + row0 + k) * 512 + chn));
;         rb[k] = __builtin_nontemporal_load((const u32x4*)(O + ((size_t)(mx * 2 + 1) * NROW + row0 + k) * 512 + chn));
;         rg[k] = __builtin_nontemporal_load((const u32x4*)(S + (size_t)(row0 + k) * NP + (mx ? C_GDN_G : C_GLA_G) + chn));
;     }
;     const float* nwp = (mx ? p.gdn_norm : p.gla_norm) + l * 128 + 8 * sub;
;     const f32x4 nw0 = *(const f32x4*)nwp, nw1 = *(const f32x4*)(nwp + 4);
; #pragma unroll
;     for (int k = 0; k < 4; ++k) {
;         float a[8], b[8], o[8], gt[8];
;         unpack8(ra[k], a); unpack8(rb[k], b); unpack8(rg[k], gt);
;         float ss = 0.f;
; #pragma unroll
;         for (int e = 0; e < 8; ++e) { o[e] = a[e] + b[e]; ss += o[e] * o[e]; }
;         ss += __shfl_xor(ss, 1); ss += __shfl_xor(ss, 2); ss += __shfl_xor(ss, 4); ss += __shfl_xor(ss, 8);
;         const float rstd = rsqrtf(ss * (1.f / 128.f) + 1e-6f);
; __global__ __launch_bounds__(512, 2) void mega(P p) {
;     ...
;         { PHASE_BEGIN const int nf = (l == 0 ? NROW : NLAT) / 16; for (int it = b1; it < nf; it += nb) { ITEM_BEGIN finish_item(q, l, it); } }
.LBB0_679:
	s_or_b64 exec, exec, s[0:1]
	s_mov_b64 s[0:1], 0
	s_waitcnt lgkmcnt(0)
	s_barrier
	s_mov_b32 s0, s19
	v_readlane_b32 s4, v254, 26
	v_readlane_b32 s0, v252, 1
	v_readlane_b32 s1, v252, 2
	s_and_b64 s[0:1], s[0:1], exec
	s_movk_i32 s0, 0x240
	v_readlane_b32 s21, v253, 0
	s_cselect_b32 s22, s0, 0x200
	v_readlane_b32 s7, v254, 29
	v_readlane_b32 s36, v254, 39
	s_cmp_ge_i32 s21, s22
	v_readlane_b32 s5, v254, 27
	v_readlane_b32 s6, v254, 28
	s_movk_i32 s7, 0x3800
	s_mov_b64 s[8:9], 0x6c3c000
	s_brev_b32 s10, 60
	v_readlane_b32 s40, v254, 43
	v_readlane_b32 s41, v254, 44
	v_readlane_b32 s48, v254, 51
	v_readlane_b32 s49, v254, 52
	v_readlane_b32 s37, v254, 40
	v_readlane_b32 s38, v254, 41
	v_readlane_b32 s39, v254, 42
	v_readlane_b32 s42, v254, 45
	v_readlane_b32 s43, v254, 46
	v_readlane_b32 s44, v254, 47
	v_readlane_b32 s45, v254, 48
	v_readlane_b32 s46, v254, 49
	v_readlane_b32 s47, v254, 50
	v_readlane_b32 s50, v254, 53
	v_readlane_b32 s51, v254, 54
	s_cbranch_scc1 .LBB0_682
	v_lshrrev_b32_e32 v118, 7, v166
	v_and_b32_e32 v119, 0x7f, v166
	v_lshrrev_b32_e32 v120, 6, v119
	v_and_b32_e32 v121, 63, v119
	v_lshlrev_b32_e32 v121, 4, v121
	v_lshlrev_b32_e32 v104, 24, v120
	v_lshl_add_u32 v104, v120, 21, v104
	v_lshl_add_u32 v104, v118, 10, v104
	v_add_u32_e32 v104, v104, v121
	v_add_u32_e32 v104, 0x483c000, v104
	v_add_u32_e32 v105, 0x900000, v104
	v_mul_u32_u24_e32 v106, 0x3800, v118
	v_lshl_add_u32 v106, v120, 12, v106
	v_add_u32_e32 v106, v106, v121
	v_add_u32_e32 v106, 0x6c3c800, v106
	v_lshlrev_b32_e32 v107, 12, v118
	v_lshl_add_u32 v107, v120, 10, v107
	v_add_u32_e32 v107, v107, v121
	v_add_u32_e32 v107, 0xea3c000, v107
	v_and_b32_e32 v123, 15, v119
	v_lshlrev_b32_e32 v123, 5, v123
	s_lshl_b32 s0, s12, 9
	v_add_u32_e32 v123, s0, v123
	v_cmp_eq_u32_e32 vcc, 0, v120
	s_and_saveexec_b64 s[2:3], vcc
	global_load_dwordx4 v[96:99], v123, s[40:41]
	global_load_dwordx4 v[100:103], v123, s[40:41] offset:16
	s_andn2_b64 exec, s[2:3], exec
	global_load_dwordx4 v[96:99], v123, s[48:49]
	global_load_dwordx4 v[100:103], v123, s[48:49] offset:16
	s_mov_b64 exec, s[2:3]
	v_mov_b32_e32 v124, 0x358637bd
	v_mov_b32_e32 v125, 0xbfb8aa3b
	s_lshl_b32 s10, s22, 2
	s_lshl_b32 s0, s6, 3
	s_add_u32 s0, s0, s21
	s_add_u32 s1, s0, s6
	s_cmp_lt_u32 s0, s10
	s_cbranch_scc0 .Lfin_generic
	s_cmp_lt_u32 s1, s10
	s_cbranch_scc1 .Lfin_generic
	s_mov_b32 s24, s21
	s_mov_b32 s7, s21
	s_lshl_b32 s0, s7, 12
	s_add_u32 s36, s4, s0
	s_addc_u32 s37, s5, 0
	s_mul_i32 s0, s7, 0xe000
	s_add_u32 s38, s4, s0
	s_addc_u32 s39, s5, 0
	global_load_dwordx4 v[0:3], v104, s[36:37] nt
	global_load_dwordx4 v[4:7], v105, s[36:37] nt
	global_load_dwordx4 v[8:11], v106, s[38:39] nt
	s_add_u32 s7, s7, s6
	s_lshl_b32 s0, s7, 12
	s_add_u32 s36, s4, s0
	s_addc_u32 s37, s5, 0
	s_mul_i32 s0, s7, 0xe000
	s_add_u32 s38, s4, s0
	s_addc_u32 s39, s5, 0
	global_load_dwordx4 v[12:15], v104, s[36:37] nt
	global_load_dwordx4 v[16:19], v105, s[36:37] nt
	global_load_dwordx4 v[20:23], v106, s[38:39] nt
	s_add_u32 s7, s7, s6
	s_lshl_b32 s0, s7, 12
	s_add_u32 s36, s4, s0
	s_addc_u32 s37, s5, 0
	s_mul_i32 s0, s7, 0xe000
	s_add_u32 s38, s4, s0
	s_addc_u32 s39, s5, 0
	global_load_dwordx4 v[24:27], v104, s[36:37] nt
	global_load_dwordx4 v[28:31], v105, s[36:37] nt
	global_load_dwordx4 v[32:35], v106, s[38:39] nt
	s_add_u32 s7, s7, s6
	s_lshl_b32 s0, s7, 12
	s_add_u32 s36, s4, s0
	s_addc_u32 s37, s5, 0
	s_mul_i32 s0, s7, 0xe000
	s_add_u32 s38, s4, s0
	s_addc_u32 s39, s5, 0
	global_load_dwordx4 v[36:39], v104, s[36:37] nt
	global_load_dwordx4 v[40:43], v105, s[36:37] nt
	global_load_dwordx4 v[44:47], v106, s[38:39] nt
	s_add_u32 s7, s7, s6
	s_waitcnt vmcnt(9)
	v_and_b32_e32 v118, 0xffff0000, v0
	v_and_b32_e32 v119, 0xffff0000, v4
	v_lshlrev_b32_e32 v0, 16, v0
	v_lshlrev_b32_e32 v120, 16, v4
	v_add_f32_e32 v0, v0, v120
	v_add_f32_e32 v4, v118, v119
	v_mul_f32_e32 v142, v0, v0
	v_fmac_f32_e32 v142, v4, v4
	v_and_b32_e32 v118, 0xffff0000, v1
	v_and_b32_e32 v119, 0xffff0000, v5
	v_lshlrev_b32_e32 v1, 16, v1
	v_lshlrev_b32_e32 v120, 16, v5
	v_add_f32_e32 v1, v1, v120
	v_add_f32_e32 v5, v118, v119
	v_fmac_f32_e32 v142, v1, v1
	v_fmac_f32_e32 v142, v5, v5
	v_and_b32_e32 v118, 0xffff0000, v2
	v_and_b32_e32 v119, 0xffff0000, v6
	v_lshlrev_b32_e32 v2, 16, v2
	v_lshlrev_b32_e32 v120, 16, v6
	v_add_f32_e32 v2, v2, v120
	v_add_f32_e32 v6, v118, v119
	v_fmac_f32_e32 v142, v2, v2
	v_fmac_f32_e32 v142, v6, v6
	v_and_b32_e32 v118, 0xffff0000, v3
	v_and_b32_e32 v119, 0xffff0000, v7
	v_lshlrev_b32_e32 v3, 16, v3
	v_lshlrev_b32_e32 v120, 16, v7
	v_add_f32_e32 v3, v3, v120
	v_add_f32_e32 v7, v118, v119
	v_fmac_f32_e32 v142, v3, v3
	v_fmac_f32_e32 v142, v7, v7
	s_nop 1
	v_add_f32_dpp v142, v142, v142 quad_perm:[1,0,3,2] row_mask:0xf bank_mask:0xf
	s_nop 1
	v_add_f32_dpp v142, v142, v142 quad_perm:[2,3,0,1] row_mask:0xf bank_mask:0xf
	s_nop 1
	v_add_f32_dpp v142, v142, v142 row_half_mirror row_mask:0xf bank_mask:0xf
	s_nop 1
	v_add_f32_dpp v142, v142, v142 row_mirror row_mask:0xf bank_mask:0xf
	v_fmamk_f32 v142, v142, 0x3c000000, v124
	v_rsq_f32_e32 v150, v142
	s_lshl_b32 s0, s24, 14
	s_add_u32 s42, s4, s0
	s_addc_u32 s43, s5, 0
	v_lshlrev_b32_e32 v118, 16, v8
	v_and_b32_e32 v119, 0xffff0000, v8
	v_mul_f32_e32 v120, v125, v118
	v_mul_f32_e32 v121, v125, v119
	v_exp_f32_e32 v120, v120
	v_exp_f32_e32 v121, v121
	v_mul_f32_e32 v0, v0, v150
	v_add_f32_e32 v120, 1.0, v120
	v_add_f32_e32 v121, 1.0, v121
	v_rcp_f32_e32 v120, v120
	v_rcp_f32_e32 v121, v121
	v_mul_f32_e32 v4, v4, v150
	v_mul_f32_e32 v0, v0, v96
	v_mul_f32_e32 v118, v118, v120
	v_mul_f32_e32 v119, v119, v121
	v_mul_f32_e32 v4, v4, v97
	v_mul_f32_e32 v0, v0, v118
; DI void unpack8(u32x4 v, float* o) { o[0] = lo16(v.x); o[1] = hi16(v.x); o[2] = lo16(v.y); o[3] = hi16(v.y); o[4] = lo16(v.z); o[5] = hi16(v.z); o[6] = lo16(v.w); o[7] = hi16(v.w); }
; DI u32x4 pack8(const float* o) { u32x4 r; r.x = pk2(o[0], o[1]); r.y = pk2(o[2], o[3]); r.z = pk2(o[4], o[5]); r.w = pk2(o[6], o[7]); return r; }
; DI float siluf(float x) { return x * __builtin_amdgcn_rcpf(1.f + __expf(-x)); }
; DI void finish_item(const P& p, int l, int r16) {
;     ...
;     for (int k = 0; k < 4; ++k) {
;         float a[8], b[8], o[8], gt[8];
;         unpack8(ra[k], a); unpack8(rb[k], b); unpack8(rg[k], gt);
;         float ss = 0.f;
; #pragma unroll
;         for (int e = 0; e < 8; ++e) { o[e] = a[e] + b[e]; ss += o[e] * o[e]; }
;         ss += __shfl_xor(ss, 1); ss += __shfl_xor(ss, 2); ss += __shfl_xor(ss, 4); ss += __shfl_xor(ss, 8);
;         const float rstd = rsqrtf(ss * (1.f / 128.f) + 1e-6f);
; #pragma unroll
;         for (int e = 0; e < 8; ++e) o[e] = o[e] * rstd * (e < 4 ? nw0[e & 3] : nw1[e & 3]) * siluf(gt[e]);
;         *(u32x4*)(Y + (size_t)(row0 + k) * DM + 512 * mx + chn) = pack8(o);
	v_mul_f32_e32 v4, v4, v119
	v_cvt_pk_bf16_f32 v154, v0, v4
	v_lshlrev_b32_e32 v118, 16, v9
	v_and_b32_e32 v119, 0xffff0000, v9
	v_mul_f32_e32 v120, v125, v118
	v_mul_f32_e32 v121, v125, v119
	v_exp_f32_e32 v120, v120
	v_exp_f32_e32 v121, v121
	v_mul_f32_e32 v1, v1, v150
	v_add_f32_e32 v120, 1.0, v120
	v_add_f32_e32 v121, 1.0, v121
	v_rcp_f32_e32 v120, v120
	v_rcp_f32_e32 v121, v121
	v_mul_f32_e32 v5, v5, v150
	v_mul_f32_e32 v1, v1, v98
	v_mul_f32_e32 v118, v118, v120
	v_mul_f32_e32 v119, v119, v121
	v_mul_f32_e32 v5, v5, v99
	v_mul_f32_e32 v1, v1, v118
	v_mul_f32_e32 v5, v5, v119
	v_cvt_pk_bf16_f32 v155, v1, v5
	v_lshlrev_b32_e32 v118, 16, v10
	v_and_b32_e32 v119, 0xffff0000, v10
	v_mul_f32_e32 v120, v125, v118
	v_mul_f32_e32 v121, v125, v119
	v_exp_f32_e32 v120, v120
	v_exp_f32_e32 v121, v121
	v_mul_f32_e32 v2, v2, v150
	v_add_f32_e32 v120, 1.0, v120
	v_add_f32_e32 v121, 1.0, v121
	v_rcp_f32_e32 v120, v120
	v_rcp_f32_e32 v121, v121
	v_mul_f32_e32 v6, v6, v150
	v_mul_f32_e32 v2, v2, v100
	v_mul_f32_e32 v118, v118, v120
	v_mul_f32_e32 v119, v119, v121
	v_mul_f32_e32 v6, v6, v101
	v_mul_f32_e32 v2, v2, v118
	v_mul_f32_e32 v6, v6, v119
	v_cvt_pk_bf16_f32 v156, v2, v6
	v_lshlrev_b32_e32 v118, 16, v11
	v_and_b32_e32 v119, 0xffff0000, v11
	v_mul_f32_e32 v120, v125, v118
	v_mul_f32_e32 v121, v125, v119
	v_exp_f32_e32 v120, v120
	v_exp_f32_e32 v121, v121
	v_mul_f32_e32 v3, v3, v150
	v_add_f32_e32 v120, 1.0, v120
	v_add_f32_e32 v121, 1.0, v121
	v_rcp_f32_e32 v120, v120
	v_rcp_f32_e32 v121, v121
	v_mul_f32_e32 v7, v7, v150
	v_mul_f32_e32 v3, v3, v102
	v_mul_f32_e32 v118, v118, v120
	v_mul_f32_e32 v119, v119, v121
	v_mul_f32_e32 v7, v7, v103
	v_mul_f32_e32 v3, v3, v118
	v_mul_f32_e32 v7, v7, v119
	v_cvt_pk_bf16_f32 v157, v3, v7
	global_store_dwordx4 v107, v[154:157], s[42:43] sc1
	s_add_u32 s24, s24, s6
	s_lshl_b32 s0, s7, 12
	s_add_u32 s36, s4, s0
	s_addc_u32 s37, s5, 0
	s_mul_i32 s0, s7, 0xe000
	s_add_u32 s38, s4, s0
	s_addc_u32 s39, s5, 0
	global_load_dwordx4 v[0:3], v104, s[36:37] nt
	global_load_dwordx4 v[4:7], v105, s[36:37] nt
	global_load_dwordx4 v[8:11], v106, s[38:39] nt
	s_add_u32 s7, s7, s6
	s_waitcnt vmcnt(10)
	v_and_b32_e32 v118, 0xffff0000, v12
	v_and_b32_e32 v119, 0xffff0000, v16
	v_lshlrev_b32_e32 v12, 16, v12
	v_lshlrev_b32_e32 v120, 16, v16
	v_add_f32_e32 v12, v12, v120
	v_add_f32_e32 v16, v118, v119
	v_mul_f32_e32 v142, v12, v12
	v_fmac_f32_e32 v142, v16, v16
	v_and_b32_e32 v118, 0xffff0000, v13
	v_and_b32_e32 v119, 0xffff0000, v17
	v_lshlrev_b32_e32 v13, 16, v13
	v_lshlrev_b32_e32 v120, 16, v17
	v_add_f32_e32 v13, v13, v120
	v_add_f32_e32 v17, v118, v119
	v_fmac_f32_e32 v142, v13, v13
	v_fmac_f32_e32 v142, v17, v17
	v_and_b32_e32 v118, 0xffff0000, v14
	v_and_b32_e32 v119, 0xffff0000, v18
	v_lshlrev_b32_e32 v14, 16, v14
	v_lshlrev_b32_e32 v120, 16, v18
	v_add_f32_e32 v14, v14, v120
	v_add_f32_e32 v18, v118, v119
	v_fmac_f32_e32 v142, v14, v14
	v_fmac_f32_e32 v142, v18, v18
	v_and_b32_e32 v118, 0xffff0000, v15
	v_and_b32_e32 v119, 0xffff0000, v19
	v_lshlrev_b32_e32 v15, 16, v15
	v_lshlrev_b32_e32 v120, 16, v19
	v_add_f32_e32 v15, v15, v120
	v_add_f32_e32 v19, v118, v119
	v_fmac_f32_e32 v142, v15, v15
	v_fmac_f32_e32 v142, v19, v19
	s_nop 1
	v_add_f32_dpp v142, v142, v142 quad_perm:[1,0,3,2] row_mask:0xf bank_mask:0xf
	s_nop 1
	v_add_f32_dpp v142, v142, v142 quad_perm:[2,3,0,1] row_mask:0xf bank_mask:0xf
	s_nop 1
	v_add_f32_dpp v142, v142, v142 row_half_mirror row_mask:0xf bank_mask:0xf
	s_nop 1
	v_add_f32_dpp v142, v142, v142 row_mirror row_mask:0xf bank_mask:0xf
	v_fmamk_f32 v142, v142, 0x3c000000, v124
	v_rsq_f32_e32 v150, v142
	s_lshl_b32 s0, s24, 14
	s_add_u32 s42, s4, s0
	s_addc_u32 s43, s5, 0
	v_lshlrev_b32_e32 v118, 16, v20
	v_and_b32_e32 v119, 0xffff0000, v20
	v_mul_f32_e32 v120, v125, v118
	v_mul_f32_e32 v121, v125, v119
	v_exp_f32_e32 v120, v120
	v_exp_f32_e32 v121, v121
	v_mul_f32_e32 v12, v12, v150
	v_add_f32_e32 v120, 1.0, v120
	v_add_f32_e32 v121, 1.0, v121
	v_rcp_f32_e32 v120, v120
	v_rcp_f32_e32 v121, v121
	v_mul_f32_e32 v16, v16, v150
	v_mul_f32_e32 v12, v12, v96
	v_mul_f32_e32 v118, v118, v120
	v_mul_f32_e32 v119, v119, v121
	v_mul_f32_e32 v16, v16, v97
	v_mul_f32_e32 v12, v12, v118
	v_mul_f32_e32 v16, v16, v119
	v_cvt_pk_bf16_f32 v158, v12, v16
	v_lshlrev_b32_e32 v118, 16, v21
	v_and_b32_e32 v119, 0xffff0000, v21
	v_mul_f32_e32 v120, v125, v118
	v_mul_f32_e32 v121, v125, v119
	v_exp_f32_e32 v120, v120
	v_exp_f32_e32 v121, v121
	v_mul_f32_e32 v13, v13, v150
	v_add_f32_e32 v120, 1.0, v120
	v_add_f32_e32 v121, 1.0, v121
	v_rcp_f32_e32 v120, v120
	v_rcp_f32_e32 v121, v121
	v_mul_f32_e32 v17, v17, v150
	v_mul_f32_e32 v13, v13, v98
	v_mul_f32_e32 v118, v118, v120
	v_mul_f32_e32 v119, v119, v121
	v_mul_f32_e32 v17, v17, v99
	v_mul_f32_e32 v13, v13, v118
	v_mul_f32_e32 v17, v17, v119
	v_cvt_pk_bf16_f32 v159, v13, v17
	v_lshlrev_b32_e32 v118, 16, v22
	v_and_b32_e32 v119, 0xffff0000, v22
	v_mul_f32_e32 v120, v125, v118
	v_mul_f32_e32 v121, v125, v119
	v_exp_f32_e32 v120, v120
	v_exp_f32_e32 v121, v121
	v_mul_f32_e32 v14, v14, v150
	v_add_f32_e32 v120, 1.0, v120
	v_add_f32_e32 v121, 1.0, v121
	v_rcp_f32_e32 v120, v120
	v_rcp_f32_e32 v121, v121
	v_mul_f32_e32 v18, v18, v150
	v_mul_f32_e32 v14, v14, v100
	v_mul_f32_e32 v118, v118, v120
	v_mul_f32_e32 v119, v119, v121
	v_mul_f32_e32 v18, v18, v101
	v_mul_f32_e32 v14, v14, v118
	v_mul_f32_e32 v18, v18, v119
	v_cvt_pk_bf16_f32 v160, v14, v18
	v_lshlrev_b32_e32 v118, 16, v23
	v_and_b32_e32 v119, 0xffff0000, v23
	v_mul_f32_e32 v120, v125, v118
	v_mul_f32_e32 v121, v125, v119
	v_exp_f32_e32 v120, v120
	v_exp_f32_e32 v121, v121
	v_mul_f32_e32 v15, v15, v150
	v_add_f32_e32 v120, 1.0, v120
	v_add_f32_e32 v121, 1.0, v121
	v_rcp_f32_e32 v120, v120
	v_rcp_f32_e32 v121, v121
	v_mul_f32_e32 v19, v19, v150
	v_mul_f32_e32 v15, v15, v102
	v_mul_f32_e32 v118, v118, v120
	v_mul_f32_e32 v119, v119, v121
	v_mul_f32_e32 v19, v19, v103
	v_mul_f32_e32 v15, v15, v118
	v_mul_f32_e32 v19, v19, v119
	v_cvt_pk_bf16_f32 v161, v15, v19
	global_store_dwordx4 v107, v[158:161], s[42:43] sc1
	s_add_u32 s24, s24, s6
	s_lshl_b32 s0, s7, 12
	s_add_u32 s36, s4, s0
	s_addc_u32 s37, s5, 0
	s_mul_i32 s0, s7, 0xe000
	s_add_u32 s38, s4, s0
	s_addc_u32 s39, s5, 0
	global_load_dwordx4 v[12:15], v104, s[36:37] nt
	global_load_dwordx4 v[16:19], v105, s[36:37] nt
	global_load_dwordx4 v[20:23], v106, s[38:39] nt
	s_add_u32 s7, s7, s6
	s_waitcnt vmcnt(11)
; DI void unpack8(u32x4 v, float* o) { o[0] = lo16(v.x); o[1] = hi16(v.x); o[2] = lo16(v.y); o[3] = hi16(v.y); o[4] = lo16(v.z); o[5] = hi16(v.z); o[6] = lo16(v.w); o[7] = hi16(v.w); }
; DI u32x4 pack8(const float* o) { u32x4 r; r.x = pk2(o[0], o[1]); r.y = pk2(o[2], o[3]); r.z = pk2(o[4], o[5]); r.w = pk2(o[6], o[7]); return r; }
; DI float siluf(float x) { return x * __builtin_amdgcn_rcpf(1.f + __expf(-x)); }
; DI void finish_item(const P& p, int l, int r16) {
;     ...
;     for (int k = 0; k < 4; ++k) {
;         float a[8], b[8], o[8], gt[8];
;         unpack8(ra[k], a); unpack8(rb[k], b); unpack8(rg[k], gt);
;         float ss = 0.f;
; #pragma unroll
;         for (int e = 0; e < 8; ++e) { o[e] = a[e] + b[e]; ss += o[e] * o[e]; }
;         ss += __shfl_xor(ss, 1); ss += __shfl_xor(ss, 2); ss += __shfl_xor(ss, 4); ss += __shfl_xor(ss, 8);
;         const float rstd = rsqrtf(ss * (1.f / 128.f) + 1e-6f);
; #pragma unroll
;         for (int e = 0; e < 8; ++e) o[e] = o[e] * rstd * (e < 4 ? nw0[e & 3] : nw1[e & 3]) * siluf(gt[e]);
;         *(u32x4*)(Y + (size_t)(row0 + k) * DM + 512 * mx + chn) = pack8(o);
	v_and_b32_e32 v118, 0xffff0000, v24
	v_and_b32_e32 v119, 0xffff0000, v28
	v_lshlrev_b32_e32 v24, 16, v24
	v_lshlrev_b32_e32 v120, 16, v28
	v_add_f32_e32 v24, v24, v120
	v_add_f32_e32 v28, v118, v119
	v_mul_f32_e32 v142, v24, v24
	v_fmac_f32_e32 v142, v28, v28
	v_and_b32_e32 v118, 0xffff0000, v25
	v_and_b32_e32 v119, 0xffff0000, v29
	v_lshlrev_b32_e32 v25, 16, v25
	v_lshlrev_b32_e32 v120, 16, v29
	v_add_f32_e32 v25, v25, v120
	v_add_f32_e32 v29, v118, v119
	v_fmac_f32_e32 v142, v25, v25
	v_fmac_f32_e32 v142, v29, v29
	v_and_b32_e32 v118, 0xffff0000, v26
	v_and_b32_e32 v119, 0xffff0000, v30
	v_lshlrev_b32_e32 v26, 16, v26
	v_lshlrev_b32_e32 v120, 16, v30
	v_add_f32_e32 v26, v26, v120
	v_add_f32_e32 v30, v118, v119
	v_fmac_f32_e32 v142, v26, v26
	v_fmac_f32_e32 v142, v30, v30
	v_and_b32_e32 v118, 0xffff0000, v27
	v_and_b32_e32 v119, 0xffff0000, v31
	v_lshlrev_b32_e32 v27, 16, v27
	v_lshlrev_b32_e32 v120, 16, v31
	v_add_f32_e32 v27, v27, v120
	v_add_f32_e32 v31, v118, v119
	v_fmac_f32_e32 v142, v27, v27
	v_fmac_f32_e32 v142, v31, v31
	s_nop 1
	v_add_f32_dpp v142, v142, v142 quad_perm:[1,0,3,2] row_mask:0xf bank_mask:0xf
	s_nop 1
	v_add_f32_dpp v142, v142, v142 quad_perm:[2,3,0,1] row_mask:0xf bank_mask:0xf
	s_nop 1
	v_add_f32_dpp v142, v142, v142 row_half_mirror row_mask:0xf bank_mask:0xf
	s_nop 1
	v_add_f32_dpp v142, v142, v142 row_mirror row_mask:0xf bank_mask:0xf
	v_fmamk_f32 v142, v142, 0x3c000000, v124
	v_rsq_f32_e32 v150, v142
	s_lshl_b32 s0, s24, 14
	s_add_u32 s42, s4, s0
	s_addc_u32 s43, s5, 0
	v_lshlrev_b32_e32 v118, 16, v32
	v_and_b32_e32 v119, 0xffff0000, v32
	v_mul_f32_e32 v120, v125, v118
	v_mul_f32_e32 v121, v125, v119
	v_exp_f32_e32 v120, v120
	v_exp_f32_e32 v121, v121
	v_mul_f32_e32 v24, v24, v150
	v_add_f32_e32 v120, 1.0, v120
	v_add_f32_e32 v121, 1.0, v121
	v_rcp_f32_e32 v120, v120
	v_rcp_f32_e32 v121, v121
	v_mul_f32_e32 v28, v28, v150
	v_mul_f32_e32 v24, v24, v96
	v_mul_f32_e32 v118, v118, v120
	v_mul_f32_e32 v119, v119, v121
	v_mul_f32_e32 v28, v28, v97
	v_mul_f32_e32 v24, v24, v118
	v_mul_f32_e32 v28, v28, v119
	v_cvt_pk_bf16_f32 v154, v24, v28
	v_lshlrev_b32_e32 v118, 16, v33
	v_and_b32_e32 v119, 0xffff0000, v33
	v_mul_f32_e32 v120, v125, v118
	v_mul_f32_e32 v121, v125, v119
	v_exp_f32_e32 v120, v120
	v_exp_f32_e32 v121, v121
	v_mul_f32_e32 v25, v25, v150
	v_add_f32_e32 v120, 1.0, v120
	v_add_f32_e32 v121, 1.0, v121
	v_rcp_f32_e32 v120, v120
	v_rcp_f32_e32 v121, v121
	v_mul_f32_e32 v29, v29, v150
	v_mul_f32_e32 v25, v25, v98
	v_mul_f32_e32 v118, v118, v120
	v_mul_f32_e32 v119, v119, v121
	v_mul_f32_e32 v29, v29, v99
	v_mul_f32_e32 v25, v25, v118
	v_mul_f32_e32 v29, v29, v119
	v_cvt_pk_bf16_f32 v155, v25, v29
	v_lshlrev_b32_e32 v118, 16, v34
	v_and_b32_e32 v119, 0xffff0000, v34
	v_mul_f32_e32 v120, v125, v118
	v_mul_f32_e32 v121, v125, v119
	v_exp_f32_e32 v120, v120
	v_exp_f32_e32 v121, v121
	v_mul_f32_e32 v26, v26, v150
	v_add_f32_e32 v120, 1.0, v120
	v_add_f32_e32 v121, 1.0, v121
	v_rcp_f32_e32 v120, v120
	v_rcp_f32_e32 v121, v121
	v_mul_f32_e32 v30, v30, v150
	v_mul_f32_e32 v26, v26, v100
	v_mul_f32_e32 v118, v118, v120
	v_mul_f32_e32 v119, v119, v121
	v_mul_f32_e32 v30, v30, v101
	v_mul_f32_e32 v26, v26, v118
	v_mul_f32_e32 v30, v30, v119
	v_cvt_pk_bf16_f32 v156, v26, v30
	v_lshlrev_b32_e32 v118, 16, v35
	v_and_b32_e32 v119, 0xffff0000, v35
	v_mul_f32_e32 v120, v125, v118
	v_mul_f32_e32 v121, v125, v119
	v_exp_f32_e32 v120, v120
	v_exp_f32_e32 v121, v121
	v_mul_f32_e32 v27, v27, v150
	v_add_f32_e32 v120, 1.0, v120
	v_add_f32_e32 v121, 1.0, v121
	v_rcp_f32_e32 v120, v120
	v_rcp_f32_e32 v121, v121
	v_mul_f32_e32 v31, v31, v150
	v_mul_f32_e32 v27, v27, v102
	v_mul_f32_e32 v118, v118, v120
	v_mul_f32_e32 v119, v119, v121
	v_mul_f32_e32 v31, v31, v103
	v_mul_f32_e32 v27, v27, v118
	v_mul_f32_e32 v31, v31, v119
	v_cvt_pk_bf16_f32 v157, v27, v31
	global_store_dwordx4 v107, v[154:157], s[42:43] sc1
	s_add_u32 s24, s24, s6
	s_lshl_b32 s0, s7, 12
	s_add_u32 s36, s4, s0
	s_addc_u32 s37, s5, 0
	s_mul_i32 s0, s7, 0xe000
	s_add_u32 s38, s4, s0
	s_addc_u32 s39, s5, 0
	global_load_dwordx4 v[24:27], v104, s[36:37] nt
	global_load_dwordx4 v[28:31], v105, s[36:37] nt
	global_load_dwordx4 v[32:35], v106, s[38:39] nt
	s_add_u32 s7, s7, s6
	s_waitcnt vmcnt(12)
; DI void unpack8(u32x4 v, float* o) { o[0] = lo16(v.x); o[1] = hi16(v.x); o[2] = lo16(v.y); o[3] = hi16(v.y); o[4] = lo16(v.z); o[5] = hi16(v.z); o[6] = lo16(v.w); o[7] = hi16(v.w); }
; DI u32x4 pack8(const float* o) { u32x4 r; r.x = pk2(o[0], o[1]); r.y = pk2(o[2], o[3]); r.z = pk2(o[4], o[5]); r.w = pk2(o[6], o[7]); return r; }
; DI float siluf(float x) { return x * __builtin_amdgcn_rcpf(1.f + __expf(-x)); }
; DI void finish_item(const P& p, int l, int r16) {
;     ...
;     for (int k = 0; k < 4; ++k) {
;         float a[8], b[8], o[8], gt[8];
;         unpack8(ra[k], a); unpack8(rb[k], b); unpack8(rg[k], gt);
;         float ss = 0.f;
; #pragma unroll
;         for (int e = 0; e < 8; ++e) { o[e] = a[e] + b[e]; ss += o[e] * o[e]; }
;         ss += __shfl_xor(ss, 1); ss += __shfl_xor(ss, 2); ss += __shfl_xor(ss, 4); ss += __shfl_xor(ss, 8);
;         const float rstd = rsqrtf(ss * (1.f / 128.f) + 1e-6f);
; #pragma unroll
;         for (int e = 0; e < 8; ++e) o[e] = o[e] * rstd * (e < 4 ? nw0[e & 3] : nw1[e & 3]) * siluf(gt[e]);
;         *(u32x4*)(Y + (size_t)(row0 + k) * DM + 512 * mx + chn) = pack8(o);
	v_and_b32_e32 v118, 0xffff0000, v36
	v_and_b32_e32 v119, 0xffff0000, v40
	v_lshlrev_b32_e32 v36, 16, v36
	v_lshlrev_b32_e32 v120, 16, v40
	v_add_f32_e32 v36, v36, v120
	v_add_f32_e32 v40, v118, v119
	v_mul_f32_e32 v142, v36, v36
	v_fmac_f32_e32 v142, v40, v40
	v_and_b32_e32 v118, 0xffff0000, v37
	v_and_b32_e32 v119, 0xffff0000, v41
	v_lshlrev_b32_e32 v37, 16, v37
	v_lshlrev_b32_e32 v120, 16, v41
	v_add_f32_e32 v37, v37, v120
	v_add_f32_e32 v41, v118, v119
	v_fmac_f32_e32 v142, v37, v37
	v_fmac_f32_e32 v142, v41, v41
	v_and_b32_e32 v118, 0xffff0000, v38
	v_and_b32_e32 v119, 0xffff0000, v42
	v_lshlrev_b32_e32 v38, 16, v38
	v_lshlrev_b32_e32 v120, 16, v42
	v_add_f32_e32 v38, v38, v120
	v_add_f32_e32 v42, v118, v119
	v_fmac_f32_e32 v142, v38, v38
	v_fmac_f32_e32 v142, v42, v42
	v_and_b32_e32 v118, 0xffff0000, v39
	v_and_b32_e32 v119, 0xffff0000, v43
	v_lshlrev_b32_e32 v39, 16, v39
	v_lshlrev_b32_e32 v120, 16, v43
	v_add_f32_e32 v39, v39, v120
	v_add_f32_e32 v43, v118, v119
	v_fmac_f32_e32 v142, v39, v39
	v_fmac_f32_e32 v142, v43, v43
	s_nop 1
	v_add_f32_dpp v142, v142, v142 quad_perm:[1,0,3,2] row_mask:0xf bank_mask:0xf
	s_nop 1
	v_add_f32_dpp v142, v142, v142 quad_perm:[2,3,0,1] row_mask:0xf bank_mask:0xf
	s_nop 1
	v_add_f32_dpp v142, v142, v142 row_half_mirror row_mask:0xf bank_mask:0xf
	s_nop 1
	v_add_f32_dpp v142, v142, v142 row_mirror row_mask:0xf bank_mask:0xf
	v_fmamk_f32 v142, v142, 0x3c000000, v124
	v_rsq_f32_e32 v150, v142
	s_lshl_b32 s0, s24, 14
	s_add_u32 s42, s4, s0
	s_addc_u32 s43, s5, 0
	v_lshlrev_b32_e32 v118, 16, v44
	v_and_b32_e32 v119, 0xffff0000, v44
	v_mul_f32_e32 v120, v125, v118
	v_mul_f32_e32 v121, v125, v119
	v_exp_f32_e32 v120, v120
	v_exp_f32_e32 v121, v121
	v_mul_f32_e32 v36, v36, v150
	v_add_f32_e32 v120, 1.0, v120
	v_add_f32_e32 v121, 1.0, v121
	v_rcp_f32_e32 v120, v120
	v_rcp_f32_e32 v121, v121
	v_mul_f32_e32 v40, v40, v150
	v_mul_f32_e32 v36, v36, v96
	v_mul_f32_e32 v118, v118, v120
	v_mul_f32_e32 v119, v119, v121
	v_mul_f32_e32 v40, v40, v97
	v_mul_f32_e32 v36, v36, v118
	v_mul_f32_e32 v40, v40, v119
	v_cvt_pk_bf16_f32 v158, v36, v40
	v_lshlrev_b32_e32 v118, 16, v45
	v_and_b32_e32 v119, 0xffff0000, v45
	v_mul_f32_e32 v120, v125, v118
	v_mul_f32_e32 v121, v125, v119
	v_exp_f32_e32 v120, v120
	v_exp_f32_e32 v121, v121
	v_mul_f32_e32 v37, v37, v150
	v_add_f32_e32 v120, 1.0, v120
	v_add_f32_e32 v121, 1.0, v121
	v_rcp_f32_e32 v120, v120
	v_rcp_f32_e32 v121, v121
	v_mul_f32_e32 v41, v41, v150
	v_mul_f32_e32 v37, v37, v98
	v_mul_f32_e32 v118, v118, v120
	v_mul_f32_e32 v119, v119, v121
	v_mul_f32_e32 v41, v41, v99
	v_mul_f32_e32 v37, v37, v118
	v_mul_f32_e32 v41, v41, v119
	v_cvt_pk_bf16_f32 v159, v37, v41
	v_lshlrev_b32_e32 v118, 16, v46
	v_and_b32_e32 v119, 0xffff0000, v46
	v_mul_f32_e32 v120, v125, v118
	v_mul_f32_e32 v121, v125, v119
	v_exp_f32_e32 v120, v120
	v_exp_f32_e32 v121, v121
	v_mul_f32_e32 v38, v38, v150
	v_add_f32_e32 v120, 1.0, v120
	v_add_f32_e32 v121, 1.0, v121
	v_rcp_f32_e32 v120, v120
	v_rcp_f32_e32 v121, v121
	v_mul_f32_e32 v42, v42, v150
	v_mul_f32_e32 v38, v38, v100
	v_mul_f32_e32 v118, v118, v120
	v_mul_f32_e32 v119, v119, v121
	v_mul_f32_e32 v42, v42, v101
	v_mul_f32_e32 v38, v38, v118
	v_mul_f32_e32 v42, v42, v119
	v_cvt_pk_bf16_f32 v160, v38, v42
	v_lshlrev_b32_e32 v118, 16, v47
	v_and_b32_e32 v119, 0xffff0000, v47
	v_mul_f32_e32 v120, v125, v118
	v_mul_f32_e32 v121, v125, v119
	v_exp_f32_e32 v120, v120
	v_exp_f32_e32 v121, v121
	v_mul_f32_e32 v39, v39, v150
	v_add_f32_e32 v120, 1.0, v120
	v_add_f32_e32 v121, 1.0, v121
	v_rcp_f32_e32 v120, v120
	v_rcp_f32_e32 v121, v121
	v_mul_f32_e32 v43, v43, v150
	v_mul_f32_e32 v39, v39, v102
	v_mul_f32_e32 v118, v118, v120
	v_mul_f32_e32 v119, v119, v121
	v_mul_f32_e32 v43, v43, v103
	v_mul_f32_e32 v39, v39, v118
	v_mul_f32_e32 v43, v43, v119
	v_cvt_pk_bf16_f32 v161, v39, v43
	global_store_dwordx4 v107, v[158:161], s[42:43] sc1
	s_add_u32 s24, s24, s6
	s_lshl_b32 s0, s7, 12
	s_add_u32 s36, s4, s0
	s_addc_u32 s37, s5, 0
	s_mul_i32 s0, s7, 0xe000
	s_add_u32 s38, s4, s0
	s_addc_u32 s39, s5, 0
	global_load_dwordx4 v[36:39], v104, s[36:37] nt
	global_load_dwordx4 v[40:43], v105, s[36:37] nt
	global_load_dwordx4 v[44:47], v106, s[38:39] nt
	s_add_u32 s7, s7, s6
	s_waitcnt vmcnt(12)
; DI void unpack8(u32x4 v, float* o) { o[0] = lo16(v.x); o[1] = hi16(v.x); o[2] = lo16(v.y); o[3] = hi16(v.y); o[4] = lo16(v.z); o[5] = hi16(v.z); o[6] = lo16(v.w); o[7] = hi16(v.w); }
; DI u32x4 pack8(const float* o) { u32x4 r; r.x = pk2(o[0], o[1]); r.y = pk2(o[2], o[3]); r.z = pk2(o[4], o[5]); r.w = pk2(o[6], o[7]); return r; }
; DI float siluf(float x) { return x * __builtin_amdgcn_rcpf(1.f + __expf(-x)); }
; DI void finish_item(const P& p, int l, int r16) {
;     ...
;     for (int k = 0; k < 4; ++k) {
;         float a[8], b[8], o[8], gt[8];
;         unpack8(ra[k], a); unpack8(rb[k], b); unpack8(rg[k], gt);
;         float ss = 0.f;
; #pragma unroll
;         for (int e = 0; e < 8; ++e) { o[e] = a[e] + b[e]; ss += o[e] * o[e]; }
;         ss += __shfl_xor(ss, 1); ss += __shfl_xor(ss, 2); ss += __shfl_xor(ss, 4); ss += __shfl_xor(ss, 8);
;         const float rstd = rsqrtf(ss * (1.f / 128.f) + 1e-6f);
; #pragma unroll
;         for (int e = 0; e < 8; ++e) o[e] = o[e] * rstd * (e < 4 ? nw0[e & 3] : nw1[e & 3]) * siluf(gt[e]);
;         *(u32x4*)(Y + (size_t)(row0 + k) * DM + 512 * mx + chn) = pack8(o);
	v_and_b32_e32 v118, 0xffff0000, v0
	v_and_b32_e32 v119, 0xffff0000, v4
	v_lshlrev_b32_e32 v0, 16, v0
	v_lshlrev_b32_e32 v120, 16, v4
	v_add_f32_e32 v0, v0, v120
	v_add_f32_e32 v4, v118, v119
	v_mul_f32_e32 v142, v0, v0
	v_fmac_f32_e32 v142, v4, v4
	v_and_b32_e32 v118, 0xffff0000, v1
	v_and_b32_e32 v119, 0xffff0000, v5
	v_lshlrev_b32_e32 v1, 16, v1
	v_lshlrev_b32_e32 v120, 16, v5
	v_add_f32_e32 v1, v1, v120
	v_add_f32_e32 v5, v118, v119
	v_fmac_f32_e32 v142, v1, v1
	v_fmac_f32_e32 v142, v5, v5
	v_and_b32_e32 v118, 0xffff0000, v2
	v_and_b32_e32 v119, 0xffff0000, v6
	v_lshlrev_b32_e32 v2, 16, v2
	v_lshlrev_b32_e32 v120, 16, v6
	v_add_f32_e32 v2, v2, v120
	v_add_f32_e32 v6, v118, v119
	v_fmac_f32_e32 v142, v2, v2
	v_fmac_f32_e32 v142, v6, v6
	v_and_b32_e32 v118, 0xffff0000, v3
	v_and_b32_e32 v119, 0xffff0000, v7
	v_lshlrev_b32_e32 v3, 16, v3
	v_lshlrev_b32_e32 v120, 16, v7
	v_add_f32_e32 v3, v3, v120
	v_add_f32_e32 v7, v118, v119
	v_fmac_f32_e32 v142, v3, v3
	v_fmac_f32_e32 v142, v7, v7
	s_nop 1
	v_add_f32_dpp v142, v142, v142 quad_perm:[1,0,3,2] row_mask:0xf bank_mask:0xf
	s_nop 1
	v_add_f32_dpp v142, v142, v142 quad_perm:[2,3,0,1] row_mask:0xf bank_mask:0xf
	s_nop 1
	v_add_f32_dpp v142, v142, v142 row_half_mirror row_mask:0xf bank_mask:0xf
	s_nop 1
	v_add_f32_dpp v142, v142, v142 row_mirror row_mask:0xf bank_mask:0xf
	v_fmamk_f32 v142, v142, 0x3c000000, v124
	v_rsq_f32_e32 v150, v142
	s_lshl_b32 s0, s24, 14
	s_add_u32 s42, s4, s0
	s_addc_u32 s43, s5, 0
	v_lshlrev_b32_e32 v118, 16, v8
	v_and_b32_e32 v119, 0xffff0000, v8
	v_mul_f32_e32 v120, v125, v118
	v_mul_f32_e32 v121, v125, v119
	v_exp_f32_e32 v120, v120
	v_exp_f32_e32 v121, v121
	v_mul_f32_e32 v0, v0, v150
	v_add_f32_e32 v120, 1.0, v120
	v_add_f32_e32 v121, 1.0, v121
	v_rcp_f32_e32 v120, v120
	v_rcp_f32_e32 v121, v121
	v_mul_f32_e32 v4, v4, v150
	v_mul_f32_e32 v0, v0, v96
	v_mul_f32_e32 v118, v118, v120
	v_mul_f32_e32 v119, v119, v121
	v_mul_f32_e32 v4, v4, v97
	v_mul_f32_e32 v0, v0, v118
	v_mul_f32_e32 v4, v4, v119
	v_cvt_pk_bf16_f32 v154, v0, v4
	v_lshlrev_b32_e32 v118, 16, v9
	v_and_b32_e32 v119, 0xffff0000, v9
	v_mul_f32_e32 v120, v125, v118
	v_mul_f32_e32 v121, v125, v119
	v_exp_f32_e32 v120, v120
	v_exp_f32_e32 v121, v121
	v_mul_f32_e32 v1, v1, v150
	v_add_f32_e32 v120, 1.0, v120
	v_add_f32_e32 v121, 1.0, v121
	v_rcp_f32_e32 v120, v120
	v_rcp_f32_e32 v121, v121
	v_mul_f32_e32 v5, v5, v150
	v_mul_f32_e32 v1, v1, v98
	v_mul_f32_e32 v118, v118, v120
	v_mul_f32_e32 v119, v119, v121
	v_mul_f32_e32 v5, v5, v99
	v_mul_f32_e32 v1, v1, v118
	v_mul_f32_e32 v5, v5, v119
	v_cvt_pk_bf16_f32 v155, v1, v5
	v_lshlrev_b32_e32 v118, 16, v10
	v_and_b32_e32 v119, 0xffff0000, v10
	v_mul_f32_e32 v120, v125, v118
	v_mul_f32_e32 v121, v125, v119
	v_exp_f32_e32 v120, v120
	v_exp_f32_e32 v121, v121
	v_mul_f32_e32 v2, v2, v150
	v_add_f32_e32 v120, 1.0, v120
	v_add_f32_e32 v121, 1.0, v121
	v_rcp_f32_e32 v120, v120
	v_rcp_f32_e32 v121, v121
	v_mul_f32_e32 v6, v6, v150
	v_mul_f32_e32 v2, v2, v100
	v_mul_f32_e32 v118, v118, v120
	v_mul_f32_e32 v119, v119, v121
	v_mul_f32_e32 v6, v6, v101
	v_mul_f32_e32 v2, v2, v118
	v_mul_f32_e32 v6, v6, v119
	v_cvt_pk_bf16_f32 v156, v2, v6
	v_lshlrev_b32_e32 v118, 16, v11
	v_and_b32_e32 v119, 0xffff0000, v11
	v_mul_f32_e32 v120, v125, v118
	v_mul_f32_e32 v121, v125, v119
	v_exp_f32_e32 v120, v120
	v_exp_f32_e32 v121, v121
	v_mul_f32_e32 v3, v3, v150
	v_add_f32_e32 v120, 1.0, v120
	v_add_f32_e32 v121, 1.0, v121
	v_rcp_f32_e32 v120, v120
	v_rcp_f32_e32 v121, v121
	v_mul_f32_e32 v7, v7, v150
	v_mul_f32_e32 v3, v3, v102
	v_mul_f32_e32 v118, v118, v120
	v_mul_f32_e32 v119, v119, v121
	v_mul_f32_e32 v7, v7, v103
	v_mul_f32_e32 v3, v3, v118
	v_mul_f32_e32 v7, v7, v119
	v_cvt_pk_bf16_f32 v157, v3, v7
	global_store_dwordx4 v107, v[154:157], s[42:43] sc1
	s_add_u32 s24, s24, s6
	s_lshl_b32 s0, s7, 12
	s_add_u32 s36, s4, s0
	s_addc_u32 s37, s5, 0
	s_mul_i32 s0, s7, 0xe000
	s_add_u32 s38, s4, s0
	s_addc_u32 s39, s5, 0
	global_load_dwordx4 v[0:3], v104, s[36:37] nt
	global_load_dwordx4 v[4:7], v105, s[36:37] nt
	global_load_dwordx4 v[8:11], v106, s[38:39] nt
	s_add_u32 s7, s7, s6
	s_waitcnt vmcnt(12)
	v_and_b32_e32 v118, 0xffff0000, v12
	v_and_b32_e32 v119, 0xffff0000, v16
	v_lshlrev_b32_e32 v12, 16, v12
	v_lshlrev_b32_e32 v120, 16, v16
	v_add_f32_e32 v12, v12, v120
	v_add_f32_e32 v16, v118, v119
	v_mul_f32_e32 v142, v12, v12
	v_fmac_f32_e32 v142, v16, v16
	v_and_b32_e32 v118, 0xffff0000, v13
	v_and_b32_e32 v119, 0xffff0000, v17
	v_lshlrev_b32_e32 v13, 16, v13
	v_lshlrev_b32_e32 v120, 16, v17
	v_add_f32_e32 v13, v13, v120
	v_add_f32_e32 v17, v118, v119
	v_fmac_f32_e32 v142, v13, v13
	v_fmac_f32_e32 v142, v17, v17
	v_and_b32_e32 v118, 0xffff0000, v14
	v_and_b32_e32 v119, 0xffff0000, v18
	v_lshlrev_b32_e32 v14, 16, v14
	v_lshlrev_b32_e32 v120, 16, v18
	v_add_f32_e32 v14, v14, v120
	v_add_f32_e32 v18, v118, v119
	v_fmac_f32_e32 v142, v14, v14
	v_fmac_f32_e32 v142, v18, v18
	v_and_b32_e32 v118, 0xffff0000, v15
	v_and_b32_e32 v119, 0xffff0000, v19
	v_lshlrev_b32_e32 v15, 16, v15
	v_lshlrev_b32_e32 v120, 16, v19
	v_add_f32_e32 v15, v15, v120
	v_add_f32_e32 v19, v118, v119
	v_fmac_f32_e32 v142, v15, v15
	v_fmac_f32_e32 v142, v19, v19
	s_nop 1
	v_add_f32_dpp v142, v142, v142 quad_perm:[1,0,3,2] row_mask:0xf bank_mask:0xf
	s_nop 1
	v_add_f32_dpp v142, v142, v142 quad_perm:[2,3,0,1] row_mask:0xf bank_mask:0xf
	s_nop 1
	v_add_f32_dpp v142, v142, v142 row_half_mirror row_mask:0xf bank_mask:0xf
	s_nop 1
	v_add_f32_dpp v142, v142, v142 row_mirror row_mask:0xf bank_mask:0xf
	v_fmamk_f32 v142, v142, 0x3c000000, v124
	v_rsq_f32_e32 v150, v142
	s_lshl_b32 s0, s24, 14
	s_add_u32 s42, s4, s0
	s_addc_u32 s43, s5, 0
; DI void unpack8(u32x4 v, float* o) { o[0] = lo16(v.x); o[1] = hi16(v.x); o[2] = lo16(v.y); o[3] = hi16(v.y); o[4] = lo16(v.z); o[5] = hi16(v.z); o[6] = lo16(v.w); o[7] = hi16(v.w); }
; DI u32x4 pack8(const float* o) { u32x4 r; r.x = pk2(o[0], o[1]); r.y = pk2(o[2], o[3]); r.z = pk2(o[4], o[5]); r.w = pk2(o[6], o[7]); return r; }
; DI float siluf(float x) { return x * __builtin_amdgcn_rcpf(1.f + __expf(-x)); }
; DI void finish_item(const P& p, int l, int r16) {
;     ...
;     for (int k = 0; k < 4; ++k) {
;         float a[8], b[8], o[8], gt[8];
;         unpack8(ra[k], a); unpack8(rb[k], b); unpack8(rg[k], gt);
;         float ss = 0.f;
; #pragma unroll
;         for (int e = 0; e < 8; ++e) { o[e] = a[e] + b[e]; ss += o[e] * o[e]; }
;         ss += __shfl_xor(ss, 1); ss += __shfl_xor(ss, 2); ss += __shfl_xor(ss, 4); ss += __shfl_xor(ss, 8);
;         const float rstd = rsqrtf(ss * (1.f / 128.f) + 1e-6f);
; #pragma unroll
;         for (int e = 0; e < 8; ++e) o[e] = o[e] * rstd * (e < 4 ? nw0[e & 3] : nw1[e & 3]) * siluf(gt[e]);
;         *(u32x4*)(Y + (size_t)(row0 + k) * DM + 512 * mx + chn) = pack8(o);
	v_lshlrev_b32_e32 v118, 16, v20
	v_and_b32_e32 v119, 0xffff0000, v20
	v_mul_f32_e32 v120, v125, v118
	v_mul_f32_e32 v121, v125, v119
	v_exp_f32_e32 v120, v120
	v_exp_f32_e32 v121, v121
	v_mul_f32_e32 v12, v12, v150
	v_add_f32_e32 v120, 1.0, v120
	v_add_f32_e32 v121, 1.0, v121
	v_rcp_f32_e32 v120, v120
	v_rcp_f32_e32 v121, v121
	v_mul_f32_e32 v16, v16, v150
	v_mul_f32_e32 v12, v12, v96
	v_mul_f32_e32 v118, v118, v120
	v_mul_f32_e32 v119, v119, v121
	v_mul_f32_e32 v16, v16, v97
	v_mul_f32_e32 v12, v12, v118
	v_mul_f32_e32 v16, v16, v119
	v_cvt_pk_bf16_f32 v158, v12, v16
	v_lshlrev_b32_e32 v118, 16, v21
	v_and_b32_e32 v119, 0xffff0000, v21
	v_mul_f32_e32 v120, v125, v118
	v_mul_f32_e32 v121, v125, v119
	v_exp_f32_e32 v120, v120
	v_exp_f32_e32 v121, v121
	v_mul_f32_e32 v13, v13, v150
	v_add_f32_e32 v120, 1.0, v120
	v_add_f32_e32 v121, 1.0, v121
	v_rcp_f32_e32 v120, v120
	v_rcp_f32_e32 v121, v121
	v_mul_f32_e32 v17, v17, v150
	v_mul_f32_e32 v13, v13, v98
	v_mul_f32_e32 v118, v118, v120
	v_mul_f32_e32 v119, v119, v121
	v_mul_f32_e32 v17, v17, v99
	v_mul_f32_e32 v13, v13, v118
	v_mul_f32_e32 v17, v17, v119
	v_cvt_pk_bf16_f32 v159, v13, v17
	v_lshlrev_b32_e32 v118, 16, v22
	v_and_b32_e32 v119, 0xffff0000, v22
	v_mul_f32_e32 v120, v125, v118
	v_mul_f32_e32 v121, v125, v119
	v_exp_f32_e32 v120, v120
	v_exp_f32_e32 v121, v121
	v_mul_f32_e32 v14, v14, v150
	v_add_f32_e32 v120, 1.0, v120
	v_add_f32_e32 v121, 1.0, v121
	v_rcp_f32_e32 v120, v120
	v_rcp_f32_e32 v121, v121
	v_mul_f32_e32 v18, v18, v150
	v_mul_f32_e32 v14, v14, v100
	v_mul_f32_e32 v118, v118, v120
	v_mul_f32_e32 v119, v119, v121
	v_mul_f32_e32 v18, v18, v101
	v_mul_f32_e32 v14, v14, v118
	v_mul_f32_e32 v18, v18, v119
	v_cvt_pk_bf16_f32 v160, v14, v18
	v_lshlrev_b32_e32 v118, 16, v23
	v_and_b32_e32 v119, 0xffff0000, v23
	v_mul_f32_e32 v120, v125, v118
	v_mul_f32_e32 v121, v125, v119
	v_exp_f32_e32 v120, v120
	v_exp_f32_e32 v121, v121
	v_mul_f32_e32 v15, v15, v150
	v_add_f32_e32 v120, 1.0, v120
	v_add_f32_e32 v121, 1.0, v121
	v_rcp_f32_e32 v120, v120
	v_rcp_f32_e32 v121, v121
	v_mul_f32_e32 v19, v19, v150
	v_mul_f32_e32 v15, v15, v102
	v_mul_f32_e32 v118, v118, v120
	v_mul_f32_e32 v119, v119, v121
	v_mul_f32_e32 v19, v19, v103
	v_mul_f32_e32 v15, v15, v118
	v_mul_f32_e32 v19, v19, v119
	v_cvt_pk_bf16_f32 v161, v15, v19
	global_store_dwordx4 v107, v[158:161], s[42:43] sc1
	s_add_u32 s24, s24, s6
	s_waitcnt vmcnt(9)
	v_and_b32_e32 v118, 0xffff0000, v24
	v_and_b32_e32 v119, 0xffff0000, v28
	v_lshlrev_b32_e32 v24, 16, v24
	v_lshlrev_b32_e32 v120, 16, v28
	v_add_f32_e32 v24, v24, v120
	v_add_f32_e32 v28, v118, v119
	v_mul_f32_e32 v142, v24, v24
	v_fmac_f32_e32 v142, v28, v28
	v_and_b32_e32 v118, 0xffff0000, v25
	v_and_b32_e32 v119, 0xffff0000, v29
	v_lshlrev_b32_e32 v25, 16, v25
	v_lshlrev_b32_e32 v120, 16, v29
	v_add_f32_e32 v25, v25, v120
	v_add_f32_e32 v29, v118, v119
	v_fmac_f32_e32 v142, v25, v25
	v_fmac_f32_e32 v142, v29, v29
	v_and_b32_e32 v118, 0xffff0000, v26
	v_and_b32_e32 v119, 0xffff0000, v30
	v_lshlrev_b32_e32 v26, 16, v26
	v_lshlrev_b32_e32 v120, 16, v30
	v_add_f32_e32 v26, v26, v120
	v_add_f32_e32 v30, v118, v119
	v_fmac_f32_e32 v142, v26, v26
	v_fmac_f32_e32 v142, v30, v30
	v_and_b32_e32 v118, 0xffff0000, v27
	v_and_b32_e32 v119, 0xffff0000, v31
	v_lshlrev_b32_e32 v27, 16, v27
	v_lshlrev_b32_e32 v120, 16, v31
	v_add_f32_e32 v27, v27, v120
	v_add_f32_e32 v31, v118, v119
	v_fmac_f32_e32 v142, v27, v27
	v_fmac_f32_e32 v142, v31, v31
	s_nop 1
	v_add_f32_dpp v142, v142, v142 quad_perm:[1,0,3,2] row_mask:0xf bank_mask:0xf
	s_nop 1
	v_add_f32_dpp v142, v142, v142 quad_perm:[2,3,0,1] row_mask:0xf bank_mask:0xf
	s_nop 1
	v_add_f32_dpp v142, v142, v142 row_half_mirror row_mask:0xf bank_mask:0xf
	s_nop 1
	v_add_f32_dpp v142, v142, v142 row_mirror row_mask:0xf bank_mask:0xf
	v_fmamk_f32 v142, v142, 0x3c000000, v124
	v_rsq_f32_e32 v150, v142
	s_lshl_b32 s0, s24, 14
	s_add_u32 s42, s4, s0
	s_addc_u32 s43, s5, 0
	v_lshlrev_b32_e32 v118, 16, v32
	v_and_b32_e32 v119, 0xffff0000, v32
	v_mul_f32_e32 v120, v125, v118
	v_mul_f32_e32 v121, v125, v119
	v_exp_f32_e32 v120, v120
	v_exp_f32_e32 v121, v121
	v_mul_f32_e32 v24, v24, v150
	v_add_f32_e32 v120, 1.0, v120
	v_add_f32_e32 v121, 1.0, v121
	v_rcp_f32_e32 v120, v120
	v_rcp_f32_e32 v121, v121
	v_mul_f32_e32 v28, v28, v150
	v_mul_f32_e32 v24, v24, v96
	v_mul_f32_e32 v118, v118, v120
	v_mul_f32_e32 v119, v119, v121
	v_mul_f32_e32 v28, v28, v97
	v_mul_f32_e32 v24, v24, v118
	v_mul_f32_e32 v28, v28, v119
	v_cvt_pk_bf16_f32 v154, v24, v28
	v_lshlrev_b32_e32 v118, 16, v33
	v_and_b32_e32 v119, 0xffff0000, v33
	v_mul_f32_e32 v120, v125, v118
	v_mul_f32_e32 v121, v125, v119
	v_exp_f32_e32 v120, v120
	v_exp_f32_e32 v121, v121
	v_mul_f32_e32 v25, v25, v150
	v_add_f32_e32 v120, 1.0, v120
	v_add_f32_e32 v121, 1.0, v121
	v_rcp_f32_e32 v120, v120
	v_rcp_f32_e32 v121, v121
	v_mul_f32_e32 v29, v29, v150
	v_mul_f32_e32 v25, v25, v98
	v_mul_f32_e32 v118, v118, v120
	v_mul_f32_e32 v119, v119, v121
	v_mul_f32_e32 v29, v29, v99
	v_mul_f32_e32 v25, v25, v118
	v_mul_f32_e32 v29, v29, v119
	v_cvt_pk_bf16_f32 v155, v25, v29
	v_lshlrev_b32_e32 v118, 16, v34
	v_and_b32_e32 v119, 0xffff0000, v34
	v_mul_f32_e32 v120, v125, v118
	v_mul_f32_e32 v121, v125, v119
	v_exp_f32_e32 v120, v120
	v_exp_f32_e32 v121, v121
	v_mul_f32_e32 v26, v26, v150
	v_add_f32_e32 v120, 1.0, v120
	v_add_f32_e32 v121, 1.0, v121
	v_rcp_f32_e32 v120, v120
	v_rcp_f32_e32 v121, v121
	v_mul_f32_e32 v30, v30, v150
	v_mul_f32_e32 v26, v26, v100
	v_mul_f32_e32 v118, v118, v120
	v_mul_f32_e32 v119, v119, v121
	v_mul_f32_e32 v30, v30, v101
	v_mul_f32_e32 v26, v26, v118
	v_mul_f32_e32 v30, v30, v119
	v_cvt_pk_bf16_f32 v156, v26, v30
	v_lshlrev_b32_e32 v118, 16, v35
	v_and_b32_e32 v119, 0xffff0000, v35
	v_mul_f32_e32 v120, v125, v118
	v_mul_f32_e32 v121, v125, v119
	v_exp_f32_e32 v120, v120
	v_exp_f32_e32 v121, v121
	v_mul_f32_e32 v27, v27, v150
	v_add_f32_e32 v120, 1.0, v120
	v_add_f32_e32 v121, 1.0, v121
	v_rcp_f32_e32 v120, v120
	v_rcp_f32_e32 v121, v121
	v_mul_f32_e32 v31, v31, v150
	v_mul_f32_e32 v27, v27, v102
	v_mul_f32_e32 v118, v118, v120
	v_mul_f32_e32 v119, v119, v121
	v_mul_f32_e32 v31, v31, v103
	v_mul_f32_e32 v27, v27, v118
	v_mul_f32_e32 v31, v31, v119
	v_cvt_pk_bf16_f32 v157, v27, v31
	global_store_dwordx4 v107, v[154:157], s[42:43] sc1
	s_add_u32 s24, s24, s6
	s_waitcnt vmcnt(6)
; DI void unpack8(u32x4 v, float* o) { o[0] = lo16(v.x); o[1] = hi16(v.x); o[2] = lo16(v.y); o[3] = hi16(v.y); o[4] = lo16(v.z); o[5] = hi16(v.z); o[6] = lo16(v.w); o[7] = hi16(v.w); }
; DI u32x4 pack8(const float* o) { u32x4 r; r.x = pk2(o[0], o[1]); r.y = pk2(o[2], o[3]); r.z = pk2(o[4], o[5]); r.w = pk2(o[6], o[7]); return r; }
; DI float siluf(float x) { return x * __builtin_amdgcn_rcpf(1.f + __expf(-x)); }
; DI void finish_item(const P& p, int l, int r16) {
;     ...
;     for (int k = 0; k < 4; ++k) {
;         float a[8], b[8], o[8], gt[8];
;         unpack8(ra[k], a); unpack8(rb[k], b); unpack8(rg[k], gt);
;         float ss = 0.f;
; #pragma unroll
;         for (int e = 0; e < 8; ++e) { o[e] = a[e] + b[e]; ss += o[e] * o[e]; }
;         ss += __shfl_xor(ss, 1); ss += __shfl_xor(ss, 2); ss += __shfl_xor(ss, 4); ss += __shfl_xor(ss, 8);
;         const float rstd = rsqrtf(ss * (1.f / 128.f) + 1e-6f);
; #pragma unroll
;         for (int e = 0; e < 8; ++e) o[e] = o[e] * rstd * (e < 4 ? nw0[e & 3] : nw1[e & 3]) * siluf(gt[e]);
;         *(u32x4*)(Y + (size_t)(row0 + k) * DM + 512 * mx + chn) = pack8(o);
	v_and_b32_e32 v118, 0xffff0000, v36
	v_and_b32_e32 v119, 0xffff0000, v40
	v_lshlrev_b32_e32 v36, 16, v36
	v_lshlrev_b32_e32 v120, 16, v40
	v_add_f32_e32 v36, v36, v120
	v_add_f32_e32 v40, v118, v119
	v_mul_f32_e32 v142, v36, v36
	v_fmac_f32_e32 v142, v40, v40
	v_and_b32_e32 v118, 0xffff0000, v37
	v_and_b32_e32 v119, 0xffff0000, v41
	v_lshlrev_b32_e32 v37, 16, v37
	v_lshlrev_b32_e32 v120, 16, v41
	v_add_f32_e32 v37, v37, v120
	v_add_f32_e32 v41, v118, v119
	v_fmac_f32_e32 v142, v37, v37
	v_fmac_f32_e32 v142, v41, v41
	v_and_b32_e32 v118, 0xffff0000, v38
	v_and_b32_e32 v119, 0xffff0000, v42
	v_lshlrev_b32_e32 v38, 16, v38
	v_lshlrev_b32_e32 v120, 16, v42
	v_add_f32_e32 v38, v38, v120
	v_add_f32_e32 v42, v118, v119
	v_fmac_f32_e32 v142, v38, v38
	v_fmac_f32_e32 v142, v42, v42
	v_and_b32_e32 v118, 0xffff0000, v39
	v_and_b32_e32 v119, 0xffff0000, v43
	v_lshlrev_b32_e32 v39, 16, v39
	v_lshlrev_b32_e32 v120, 16, v43
	v_add_f32_e32 v39, v39, v120
	v_add_f32_e32 v43, v118, v119
	v_fmac_f32_e32 v142, v39, v39
	v_fmac_f32_e32 v142, v43, v43
	s_nop 1
	v_add_f32_dpp v142, v142, v142 quad_perm:[1,0,3,2] row_mask:0xf bank_mask:0xf
	s_nop 1
	v_add_f32_dpp v142, v142, v142 quad_perm:[2,3,0,1] row_mask:0xf bank_mask:0xf
	s_nop 1
	v_add_f32_dpp v142, v142, v142 row_half_mirror row_mask:0xf bank_mask:0xf
	s_nop 1
	v_add_f32_dpp v142, v142, v142 row_mirror row_mask:0xf bank_mask:0xf
	v_fmamk_f32 v142, v142, 0x3c000000, v124
	v_rsq_f32_e32 v150, v142
	s_lshl_b32 s0, s24, 14
	s_add_u32 s42, s4, s0
	s_addc_u32 s43, s5, 0
	v_lshlrev_b32_e32 v118, 16, v44
	v_and_b32_e32 v119, 0xffff0000, v44
	v_mul_f32_e32 v120, v125, v118
	v_mul_f32_e32 v121, v125, v119
	v_exp_f32_e32 v120, v120
	v_exp_f32_e32 v121, v121
	v_mul_f32_e32 v36, v36, v150
	v_add_f32_e32 v120, 1.0, v120
	v_add_f32_e32 v121, 1.0, v121
	v_rcp_f32_e32 v120, v120
	v_rcp_f32_e32 v121, v121
	v_mul_f32_e32 v40, v40, v150
	v_mul_f32_e32 v36, v36, v96
	v_mul_f32_e32 v118, v118, v120
	v_mul_f32_e32 v119, v119, v121
	v_mul_f32_e32 v40, v40, v97
	v_mul_f32_e32 v36, v36, v118
	v_mul_f32_e32 v40, v40, v119
	v_cvt_pk_bf16_f32 v158, v36, v40
	v_lshlrev_b32_e32 v118, 16, v45
	v_and_b32_e32 v119, 0xffff0000, v45
	v_mul_f32_e32 v120, v125, v118
	v_mul_f32_e32 v121, v125, v119
	v_exp_f32_e32 v120, v120
	v_exp_f32_e32 v121, v121
	v_mul_f32_e32 v37, v37, v150
	v_add_f32_e32 v120, 1.0, v120
	v_add_f32_e32 v121, 1.0, v121
	v_rcp_f32_e32 v120, v120
	v_rcp_f32_e32 v121, v121
	v_mul_f32_e32 v41, v41, v150
	v_mul_f32_e32 v37, v37, v98
	v_mul_f32_e32 v118, v118, v120
	v_mul_f32_e32 v119, v119, v121
	v_mul_f32_e32 v41, v41, v99
	v_mul_f32_e32 v37, v37, v118
	v_mul_f32_e32 v41, v41, v119
	v_cvt_pk_bf16_f32 v159, v37, v41
	v_lshlrev_b32_e32 v118, 16, v46
	v_and_b32_e32 v119, 0xffff0000, v46
	v_mul_f32_e32 v120, v125, v118
	v_mul_f32_e32 v121, v125, v119
	v_exp_f32_e32 v120, v120
	v_exp_f32_e32 v121, v121
	v_mul_f32_e32 v38, v38, v150
	v_add_f32_e32 v120, 1.0, v120
	v_add_f32_e32 v121, 1.0, v121
	v_rcp_f32_e32 v120, v120
	v_rcp_f32_e32 v121, v121
	v_mul_f32_e32 v42, v42, v150
	v_mul_f32_e32 v38, v38, v100
	v_mul_f32_e32 v118, v118, v120
	v_mul_f32_e32 v119, v119, v121
	v_mul_f32_e32 v42, v42, v101
	v_mul_f32_e32 v38, v38, v118
	v_mul_f32_e32 v42, v42, v119
	v_cvt_pk_bf16_f32 v160, v38, v42
	v_lshlrev_b32_e32 v118, 16, v47
	v_and_b32_e32 v119, 0xffff0000, v47
	v_mul_f32_e32 v120, v125, v118
	v_mul_f32_e32 v121, v125, v119
	v_exp_f32_e32 v120, v120
	v_exp_f32_e32 v121, v121
	v_mul_f32_e32 v39, v39, v150
	v_add_f32_e32 v120, 1.0, v120
	v_add_f32_e32 v121, 1.0, v121
	v_rcp_f32_e32 v120, v120
	v_rcp_f32_e32 v121, v121
	v_mul_f32_e32 v43, v43, v150
	v_mul_f32_e32 v39, v39, v102
	v_mul_f32_e32 v118, v118, v120
	v_mul_f32_e32 v119, v119, v121
	v_mul_f32_e32 v43, v43, v103
	v_mul_f32_e32 v39, v39, v118
	v_mul_f32_e32 v43, v43, v119
	v_cvt_pk_bf16_f32 v161, v39, v43
	global_store_dwordx4 v107, v[158:161], s[42:43] sc1
	s_add_u32 s24, s24, s6
	s_waitcnt vmcnt(3)
	v_and_b32_e32 v118, 0xffff0000, v0
	v_and_b32_e32 v119, 0xffff0000, v4
	v_lshlrev_b32_e32 v0, 16, v0
	v_lshlrev_b32_e32 v120, 16, v4
	v_add_f32_e32 v0, v0, v120
	v_add_f32_e32 v4, v118, v119
	v_mul_f32_e32 v142, v0, v0
	v_fmac_f32_e32 v142, v4, v4
	v_and_b32_e32 v118, 0xffff0000, v1
	v_and_b32_e32 v119, 0xffff0000, v5
	v_lshlrev_b32_e32 v1, 16, v1
	v_lshlrev_b32_e32 v120, 16, v5
	v_add_f32_e32 v1, v1, v120
	v_add_f32_e32 v5, v118, v119
	v_fmac_f32_e32 v142, v1, v1
	v_fmac_f32_e32 v142, v5, v5
	v_and_b32_e32 v118, 0xffff0000, v2
	v_and_b32_e32 v119, 0xffff0000, v6
	v_lshlrev_b32_e32 v2, 16, v2
	v_lshlrev_b32_e32 v120, 16, v6
	v_add_f32_e32 v2, v2, v120
	v_add_f32_e32 v6, v118, v119
	v_fmac_f32_e32 v142, v2, v2
	v_fmac_f32_e32 v142, v6, v6
	v_and_b32_e32 v118, 0xffff0000, v3
	v_and_b32_e32 v119, 0xffff0000, v7
	v_lshlrev_b32_e32 v3, 16, v3
	v_lshlrev_b32_e32 v120, 16, v7
	v_add_f32_e32 v3, v3, v120
	v_add_f32_e32 v7, v118, v119
	v_fmac_f32_e32 v142, v3, v3
	v_fmac_f32_e32 v142, v7, v7
	s_nop 1
	v_add_f32_dpp v142, v142, v142 quad_perm:[1,0,3,2] row_mask:0xf bank_mask:0xf
	s_nop 1
	v_add_f32_dpp v142, v142, v142 quad_perm:[2,3,0,1] row_mask:0xf bank_mask:0xf
	s_nop 1
	v_add_f32_dpp v142, v142, v142 row_half_mirror row_mask:0xf bank_mask:0xf
	s_nop 1
	v_add_f32_dpp v142, v142, v142 row_mirror row_mask:0xf bank_mask:0xf
	v_fmamk_f32 v142, v142, 0x3c000000, v124
	v_rsq_f32_e32 v150, v142
	s_lshl_b32 s0, s24, 14
	s_add_u32 s42, s4, s0
	s_addc_u32 s43, s5, 0
	v_lshlrev_b32_e32 v118, 16, v8
	v_and_b32_e32 v119, 0xffff0000, v8
	v_mul_f32_e32 v120, v125, v118
	v_mul_f32_e32 v121, v125, v119
	v_exp_f32_e32 v120, v120
	v_exp_f32_e32 v121, v121
	v_mul_f32_e32 v0, v0, v150
	v_add_f32_e32 v120, 1.0, v120
; DI void unpack8(u32x4 v, float* o) { o[0] = lo16(v.x); o[1] = hi16(v.x); o[2] = lo16(v.y); o[3] = hi16(v.y); o[4] = lo16(v.z); o[5] = hi16(v.z); o[6] = lo16(v.w); o[7] = hi16(v.w); }
; DI u32x4 pack8(const float* o) { u32x4 r; r.x = pk2(o[0], o[1]); r.y = pk2(o[2], o[3]); r.z = pk2(o[4], o[5]); r.w = pk2(o[6], o[7]); return r; }
; DI float siluf(float x) { return x * __builtin_amdgcn_rcpf(1.f + __expf(-x)); }
; DI int otid() { int t = threadIdx.x; asm volatile("" : "+v"(t)); return t; }
; DI void finish_item(const P& p, int l, int r16) {
;     ...
;     const int tid = otid(); const int row0 = r16 * 16 + (tid >> 7) * 4, u = tid & 127, mx = u >> 6, hh = (u >> 4) & 3, sub = u & 15;
;     const int chn = 128 * hh + 8 * sub;
;     u32x4 ra[4], rb[4], rg[4];
; #pragma unroll
;     for (int k = 0; k < 4; ++k) {
;         ra[k] = __builtin_nontemporal_load((const u32x4*)(O + ((size_t)(mx * 2 + 0) * NROW + row0 + k) * 512 + chn));
;         rb[k] = __builtin_nontemporal_load((const u32x4*)(O + ((size_t)(mx * 2 + 1) * NROW + row0 + k) * 512 + chn));
;         rg[k] = __builtin_nontemporal_load((const u32x4*)(S + (size_t)(row0 + k) * NP + (mx ? C_GDN_G : C_GLA_G) + chn));
;     }
;     const float* nwp = (mx ? p.gdn_norm : p.gla_norm) + l * 128 + 8 * sub;
;     const f32x4 nw0 = *(const f32x4*)nwp, nw1 = *(const f32x4*)(nwp + 4);
; #pragma unroll
;     for (int k = 0; k < 4; ++k) {
;         float a[8], b[8], o[8], gt[8];
;         unpack8(ra[k], a); unpack8(rb[k], b); unpack8(rg[k], gt);
;         float ss = 0.f;
; #pragma unroll
;         for (int e = 0; e < 8; ++e) { o[e] = a[e] + b[e]; ss += o[e] * o[e]; }
;         ss += __shfl_xor(ss, 1); ss += __shfl_xor(ss, 2); ss += __shfl_xor(ss, 4); ss += __shfl_xor(ss, 8);
;         const float rstd = rsqrtf(ss * (1.f / 128.f) + 1e-6f);
; #pragma unroll
;         for (int e = 0; e < 8; ++e) o[e] = o[e] * rstd * (e < 4 ? nw0[e & 3] : nw1[e & 3]) * siluf(gt[e]);
;         *(u32x4*)(Y + (size_t)(row0 + k) * DM + 512 * mx + chn) = pack8(o);
;     }
; }
	v_add_f32_e32 v121, 1.0, v121
	v_rcp_f32_e32 v120, v120
	v_rcp_f32_e32 v121, v121
	v_mul_f32_e32 v4, v4, v150
	v_mul_f32_e32 v0, v0, v96
	v_mul_f32_e32 v118, v118, v120
	v_mul_f32_e32 v119, v119, v121
	v_mul_f32_e32 v4, v4, v97
	v_mul_f32_e32 v0, v0, v118
	v_mul_f32_e32 v4, v4, v119
	v_cvt_pk_bf16_f32 v154, v0, v4
	v_lshlrev_b32_e32 v118, 16, v9
	v_and_b32_e32 v119, 0xffff0000, v9
	v_mul_f32_e32 v120, v125, v118
	v_mul_f32_e32 v121, v125, v119
	v_exp_f32_e32 v120, v120
	v_exp_f32_e32 v121, v121
	v_mul_f32_e32 v1, v1, v150
	v_add_f32_e32 v120, 1.0, v120
	v_add_f32_e32 v121, 1.0, v121
	v_rcp_f32_e32 v120, v120
	v_rcp_f32_e32 v121, v121
	v_mul_f32_e32 v5, v5, v150
	v_mul_f32_e32 v1, v1, v98
	v_mul_f32_e32 v118, v118, v120
	v_mul_f32_e32 v119, v119, v121
	v_mul_f32_e32 v5, v5, v99
	v_mul_f32_e32 v1, v1, v118
	v_mul_f32_e32 v5, v5, v119
	v_cvt_pk_bf16_f32 v155, v1, v5
	v_lshlrev_b32_e32 v118, 16, v10
	v_and_b32_e32 v119, 0xffff0000, v10
	v_mul_f32_e32 v120, v125, v118
	v_mul_f32_e32 v121, v125, v119
	v_exp_f32_e32 v120, v120
	v_exp_f32_e32 v121, v121
	v_mul_f32_e32 v2, v2, v150
	v_add_f32_e32 v120, 1.0, v120
	v_add_f32_e32 v121, 1.0, v121
	v_rcp_f32_e32 v120, v120
	v_rcp_f32_e32 v121, v121
	v_mul_f32_e32 v6, v6, v150
	v_mul_f32_e32 v2, v2, v100
	v_mul_f32_e32 v118, v118, v120
	v_mul_f32_e32 v119, v119, v121
	v_mul_f32_e32 v6, v6, v101
	v_mul_f32_e32 v2, v2, v118
	v_mul_f32_e32 v6, v6, v119
	v_cvt_pk_bf16_f32 v156, v2, v6
	v_lshlrev_b32_e32 v118, 16, v11
	v_and_b32_e32 v119, 0xffff0000, v11
	v_mul_f32_e32 v120, v125, v118
	v_mul_f32_e32 v121, v125, v119
	v_exp_f32_e32 v120, v120
	v_exp_f32_e32 v121, v121
	v_mul_f32_e32 v3, v3, v150
	v_add_f32_e32 v120, 1.0, v120
	v_add_f32_e32 v121, 1.0, v121
	v_rcp_f32_e32 v120, v120
	v_rcp_f32_e32 v121, v121
	v_mul_f32_e32 v7, v7, v150
	v_mul_f32_e32 v3, v3, v102
	v_mul_f32_e32 v118, v118, v120
	v_mul_f32_e32 v119, v119, v121
	v_mul_f32_e32 v7, v7, v103
	v_mul_f32_e32 v3, v3, v118
	v_mul_f32_e32 v7, v7, v119
	v_cvt_pk_bf16_f32 v157, v3, v7
	global_store_dwordx4 v107, v[154:157], s[42:43] sc1
	s_add_u32 s24, s24, s6
	s_branch .Lfin_done
.Lfin_generic:
	s_mov_b32 s24, s21
	s_cmp_lt_u32 s24, s10
	s_cbranch_scc0 .Lfin_done
.Lfin_gloop:
	s_lshl_b32 s0, s24, 12
	s_add_u32 s36, s4, s0
	s_addc_u32 s37, s5, 0
	s_mul_i32 s0, s24, 0xe000
	s_add_u32 s38, s4, s0
	s_addc_u32 s39, s5, 0
	global_load_dwordx4 v[0:3], v104, s[36:37] nt
	global_load_dwordx4 v[4:7], v105, s[36:37] nt
	global_load_dwordx4 v[8:11], v106, s[38:39] nt
	s_waitcnt vmcnt(0)
	v_and_b32_e32 v118, 0xffff0000, v0
	v_and_b32_e32 v119, 0xffff0000, v4
	v_lshlrev_b32_e32 v0, 16, v0
	v_lshlrev_b32_e32 v120, 16, v4
	v_add_f32_e32 v0, v0, v120
	v_add_f32_e32 v4, v118, v119
	v_mul_f32_e32 v142, v0, v0
	v_fmac_f32_e32 v142, v4, v4
	v_and_b32_e32 v118, 0xffff0000, v1
	v_and_b32_e32 v119, 0xffff0000, v5
	v_lshlrev_b32_e32 v1, 16, v1
	v_lshlrev_b32_e32 v120, 16, v5
	v_add_f32_e32 v1, v1, v120
	v_add_f32_e32 v5, v118, v119
	v_fmac_f32_e32 v142, v1, v1
	v_fmac_f32_e32 v142, v5, v5
	v_and_b32_e32 v118, 0xffff0000, v2
	v_and_b32_e32 v119, 0xffff0000, v6
	v_lshlrev_b32_e32 v2, 16, v2
	v_lshlrev_b32_e32 v120, 16, v6
	v_add_f32_e32 v2, v2, v120
	v_add_f32_e32 v6, v118, v119
	v_fmac_f32_e32 v142, v2, v2
	v_fmac_f32_e32 v142, v6, v6
	v_and_b32_e32 v118, 0xffff0000, v3
	v_and_b32_e32 v119, 0xffff0000, v7
	v_lshlrev_b32_e32 v3, 16, v3
	v_lshlrev_b32_e32 v120, 16, v7
	v_add_f32_e32 v3, v3, v120
	v_add_f32_e32 v7, v118, v119
	v_fmac_f32_e32 v142, v3, v3
	v_fmac_f32_e32 v142, v7, v7
	s_nop 1
	v_add_f32_dpp v142, v142, v142 quad_perm:[1,0,3,2] row_mask:0xf bank_mask:0xf
	s_nop 1
	v_add_f32_dpp v142, v142, v142 quad_perm:[2,3,0,1] row_mask:0xf bank_mask:0xf
	s_nop 1
	v_add_f32_dpp v142, v142, v142 row_half_mirror row_mask:0xf bank_mask:0xf
	s_nop 1
	v_add_f32_dpp v142, v142, v142 row_mirror row_mask:0xf bank_mask:0xf
	v_fmamk_f32 v142, v142, 0x3c000000, v124
	v_rsq_f32_e32 v150, v142
	s_lshl_b32 s0, s24, 14
	s_add_u32 s42, s4, s0
	s_addc_u32 s43, s5, 0
	v_lshlrev_b32_e32 v118, 16, v8
	v_and_b32_e32 v119, 0xffff0000, v8
	v_mul_f32_e32 v120, v125, v118
	v_mul_f32_e32 v121, v125, v119
	v_exp_f32_e32 v120, v120
	v_exp_f32_e32 v121, v121
	v_mul_f32_e32 v0, v0, v150
	v_add_f32_e32 v120, 1.0, v120
	v_add_f32_e32 v121, 1.0, v121
	v_rcp_f32_e32 v120, v120
	v_rcp_f32_e32 v121, v121
	v_mul_f32_e32 v4, v4, v150
	v_mul_f32_e32 v0, v0, v96
	v_mul_f32_e32 v118, v118, v120
	v_mul_f32_e32 v119, v119, v121
	v_mul_f32_e32 v4, v4, v97
	v_mul_f32_e32 v0, v0, v118
	v_mul_f32_e32 v4, v4, v119
	v_cvt_pk_bf16_f32 v154, v0, v4
	v_lshlrev_b32_e32 v118, 16, v9
	v_and_b32_e32 v119, 0xffff0000, v9
	v_mul_f32_e32 v120, v125, v118
	v_mul_f32_e32 v121, v125, v119
	v_exp_f32_e32 v120, v120
	v_exp_f32_e32 v121, v121
	v_mul_f32_e32 v1, v1, v150
	v_add_f32_e32 v120, 1.0, v120
	v_add_f32_e32 v121, 1.0, v121
	v_rcp_f32_e32 v120, v120
	v_rcp_f32_e32 v121, v121
	v_mul_f32_e32 v5, v5, v150
	v_mul_f32_e32 v1, v1, v98
	v_mul_f32_e32 v118, v118, v120
	v_mul_f32_e32 v119, v119, v121
	v_mul_f32_e32 v5, v5, v99
	v_mul_f32_e32 v1, v1, v118
	v_mul_f32_e32 v5, v5, v119
	v_cvt_pk_bf16_f32 v155, v1, v5
	v_lshlrev_b32_e32 v118, 16, v10
	v_and_b32_e32 v119, 0xffff0000, v10
	v_mul_f32_e32 v120, v125, v118
	v_mul_f32_e32 v121, v125, v119
	v_exp_f32_e32 v120, v120
	v_exp_f32_e32 v121, v121
	v_mul_f32_e32 v2, v2, v150
	v_add_f32_e32 v120, 1.0, v120
	v_add_f32_e32 v121, 1.0, v121
	v_rcp_f32_e32 v120, v120
	v_rcp_f32_e32 v121, v121
	v_mul_f32_e32 v6, v6, v150
	v_mul_f32_e32 v2, v2, v100
	v_mul_f32_e32 v118, v118, v120
	v_mul_f32_e32 v119, v119, v121
	v_mul_f32_e32 v6, v6, v101
	v_mul_f32_e32 v2, v2, v118
	v_mul_f32_e32 v6, v6, v119
	v_cvt_pk_bf16_f32 v156, v2, v6
	v_lshlrev_b32_e32 v118, 16, v11
	v_and_b32_e32 v119, 0xffff0000, v11
	v_mul_f32_e32 v120, v125, v118
	v_mul_f32_e32 v121, v125, v119
	v_exp_f32_e32 v120, v120
	v_exp_f32_e32 v121, v121
	v_mul_f32_e32 v3, v3, v150
	v_add_f32_e32 v120, 1.0, v120
	v_add_f32_e32 v121, 1.0, v121
	v_rcp_f32_e32 v120, v120
	v_rcp_f32_e32 v121, v121
	v_mul_f32_e32 v7, v7, v150
	v_mul_f32_e32 v3, v3, v102
	v_mul_f32_e32 v118, v118, v120
	v_mul_f32_e32 v119, v119, v121
	v_mul_f32_e32 v7, v7, v103
	v_mul_f32_e32 v3, v3, v118
	v_mul_f32_e32 v7, v7, v119
	v_cvt_pk_bf16_f32 v157, v3, v7
	global_store_dwordx4 v107, v[154:157], s[42:43] sc1
	s_add_u32 s24, s24, s6
	s_cmp_lt_u32 s24, s10
	s_cbranch_scc1 .Lfin_gloop
